# CN: CL + deferred transposes chunks in the layer-0 mixer tail made 4x finer (1280 chunks of 8 tiles instead of 320 of 32)
# speedup vs baseline: 1.0170x; 1.0170x over previous
; __global__ void __launch_bounds__(256, 2) fwd_megakernel(Params p) {
;     ...
;               if (l != 0 || rep != 0) break;
;               int j = atomicAdd((int*)(ws + OFF_CNT) + 16, 1);
;               if (j < TR_DEFER / TR_CHUNK) job = -2 - j;
;               break;
;             }
;           }
;           s_job = job;
.LBB0_696:
	s_andn2_saveexec_b64 s[4:5], s[10:11]
	s_cbranch_execz .LBB0_700
	v_readlane_b32 s10, v237, 29
	v_readlane_b32 s11, v237, 30
	v_mov_b32_e32 v3, -1
	s_andn2_b64 vcc, exec, s[10:11]
	s_cbranch_vccnz .LBB0_699
	v_readlane_b32 s10, v237, 23
	v_readlane_b32 s11, v237, 24
	s_movk_i32 s2, 0x500
	s_nop 0
	v_mov_b64_e32 v[2:3], s[10:11]
	global_atomic_add v2, v[2:3], v198, off sc0
	s_waitcnt vmcnt(0) lgkmcnt(0)
	v_sub_u32_e32 v3, -2, v2
	v_cmp_gt_i32_e32 vcc, s2, v2
	s_nop 1
	v_cndmask_b32_e32 v3, -1, v3, vcc

; __device__ __forceinline__ TrJob tr_decode(const Params& p, char* ws, int job) {
;   TrJob t;
;   int l = job / TJ_PER_LAYER, rj = job % TJ_PER_LAYER;
;   if (rj < 640) {
;     t.src = p.w_in + (size_t)l * 1024 * 2560; t.K = 1024; t.N = 2560; t.kt = rj / 40; t.nt = rj % 40;
;     t.dst = (u16*)(ws + OFF_WINT) + (size_t)l * 2560 * 1024; t.mode = 0;
;   } else if (rj < 896) {
;     rj -= 640;
;     t.src = p.w_out + (size_t)l * 1024 * 1024; t.K = 1024; t.N = 1024; t.kt = rj / 16; t.nt = rj % 16;
;     t.dst = (u16*)(ws + OFF_WOUTT) + (size_t)l * 1024 * 1024; t.mode = 0;
;   } else {
;     rj -= 896;
;     int e = rj / 1536, q = rj % 1536;
;     size_t eo = (size_t)(l * 16 + e);
;     if (q < 512) {
;       t.src = p.w_gate + eo * 1024 * 2048; t.K = 1024; t.N = 2048; t.kt = q / 32; t.nt = q % 32;
;       t.dst = (u16*)(ws + OFF_WGUT) + eo * 4096 * 1024; t.mode = 1;
;     } else if (q < 1024) {
;       q -= 512;
;       t.src = p.w_up + eo * 1024 * 2048; t.K = 1024; t.N = 2048; t.kt = q / 32; t.nt = q % 32;
;       t.dst = (u16*)(ws + OFF_WGUT) + eo * 4096 * 1024; t.mode = 2;
;     } else {
;       q -= 1024;
;       t.src = p.w_down + eo * 2048 * 1024; t.K = 2048; t.N = 1024; t.kt = q / 16; t.nt = q % 16;
;       t.dst = (u16*)(ws + OFF_WDT) + eo * 1024 * 2048; t.mode = 0;
;     }
;   }
; __global__ void __launch_bounds__(256, 2) fwd_megakernel(Params p) {
;     ...
;         if (job < -1) {
;           const int c0_ = J_DEFER + (-2 - job) * TR_CHUNK;
;           p0_transposes(p, smem, 0, 1, c0_, c0_ + TR_CHUNK);
;           continue;
.LBB0_716:
	s_lshl_b32 s20, s10, 3
	s_sub_i32 s22, 0x9ef0, s20
	s_sub_i32 s2, 0x9ef8, s20
	s_cmp_lt_i32 s22, s2
	v_mov_b32_e32 v2, v172
	s_mov_b64 s[0:1], s[58:59]
	s_cselect_b64 s[4:5], -1, 0
	s_cmp_ge_i32 s22, s2
	s_cbranch_scc1 .LBB0_750
	s_mul_hi_i32 s10, s22, 0x5254e78f
	s_lshr_b32 s11, s10, 31
	s_ashr_i32 s10, s10, 13
	s_add_i32 s10, s10, s11
	s_mul_i32 s11, s10, 0x6380
	s_sub_i32 s21, s22, s11
	s_cmpk_gt_i32 s21, 0x27f
	s_mov_b64 s[16:17], -1
	s_cbranch_scc0 .LBB0_731
	s_cmpk_gt_u32 s21, 0x37f
	s_cbranch_scc0 .LBB0_728
	s_add_i32 s11, s21, 0xfc80
	s_and_b32 s12, s11, 0xffff
	s_mul_i32 s12, s12, 0xaaab
	s_lshr_b32 s12, s12, 26
	s_mul_i32 s13, s12, 0x600
	s_sub_i32 s11, s11, s13
	s_and_b32 s24, s11, 0xffff
	s_lshl_b32 s11, s10, 4
	s_add_i32 s16, s11, s12
	s_ashr_i32 s17, s16, 31
	s_cmpk_gt_u32 s24, 0x1ff
	s_mov_b64 s[18:19], -1
	s_cbranch_scc0 .LBB0_725
	s_lshl_b64 s[18:19], s[16:17], 23
	s_cmpk_gt_u32 s24, 0x3ff
	s_mov_b64 s[14:15], -1
	s_cbranch_scc0 .LBB0_722
	v_readlane_b32 s40, v238, 25
	s_add_i32 s11, s24, 0xfffffc00
	v_readlane_b32 s46, v238, 31
	v_readlane_b32 s47, v238, 32
	s_add_u32 s12, s46, s18
	v_readlane_b32 s41, v238, 26
	v_readlane_b32 s42, v238, 27
	v_readlane_b32 s43, v238, 28
	v_readlane_b32 s44, v238, 29
	v_readlane_b32 s45, v238, 30
	s_addc_u32 s13, s47, s19
	s_lshr_b32 s23, s11, 4
	s_and_b32 s11, s24, 15
	s_mov_b64 s[14:15], 0

; __device__ __forceinline__ void tr_load(const Params& p, char* ws, int job, int tid, float4 (&r)[4]) {
;   TrJob t = tr_decode(p, ws, job);
;   const int c4 = tid & 15, rr = tid >> 4;
;   const float* s0 = t.src + (size_t)(t.kt * 64 + rr) * t.N + t.nt * 64 + c4 * 4;
; #pragma unroll
;   for (int pp = 0; pp < 4; ++pp) {
;     f32x4 v_ = __builtin_nontemporal_load((const f32x4*)(s0 + (size_t)(16 * pp) * t.N));
;     r[pp] = make_float4(v_[0], v_[1], v_[2], v_[3]);
;   }
; }
; __device__ __forceinline__ void p0_transposes(const Params& p, char* smem, int bid, int nb, int jlo, int jhi) {
;     ...
;   int j = jlo + bid * 2;
;   if (j < jhi) { tr_load(p, ws, j, tid, c0); tr_load(p, ws, j + 1, tid, c1); }
.LBB0_733:
	v_ashrrev_i32_e32 v3, 4, v2
	v_lshl_add_u32 v0, s23, 6, v3
	v_ashrrev_i32_e32 v4, 31, v0
	v_mul_lo_u32 v6, s14, v4
	v_mul_lo_u32 v7, s15, v0
	v_mad_u64_u32 v[4:5], s[16:17], s14, v0, 0
	v_add3_u32 v5, v5, v6, v7
	s_lshl_b32 s10, s11, 6
	v_lshlrev_b32_e32 v0, 2, v2
	v_lshl_add_u64 v[4:5], v[4:5], 2, s[12:13]
	s_ashr_i32 s11, s10, 31
	v_and_b32_e32 v0, 60, v0
	v_lshl_add_u64 v[4:5], s[10:11], 2, v[4:5]
	v_lshlrev_b32_e32 v0, 2, v0
	v_lshl_add_u64 v[4:5], v[4:5], 0, v[0:1]
	s_lshl_b64 s[10:11], s[14:15], 6
	v_lshl_add_u64 v[6:7], v[4:5], 0, s[10:11]
	global_load_dwordx4 v[18:21], v[4:5], off nt
	global_load_dwordx4 v[22:25], v[6:7], off nt
	v_lshl_add_u64 v[4:5], v[6:7], 0, s[10:11]
	v_lshl_add_u64 v[6:7], v[4:5], 0, s[10:11]
	global_load_dwordx4 v[26:29], v[4:5], off nt
	global_load_dwordx4 v[30:33], v[6:7], off nt
	s_sub_i32 s11, 0x9ef1, s20
	s_mul_hi_i32 s10, s11, 0x5254e78f
	s_lshr_b32 s12, s10, 31
	s_ashr_i32 s10, s10, 13
	s_add_i32 s10, s10, s12
	s_mul_i32 s12, s10, 0x6380
	s_sub_i32 s20, s11, s12
	s_cmpk_gt_i32 s20, 0x27f
	s_mov_b64 s[16:17], -1
	s_cbranch_scc0 .LBB0_747
	s_cmpk_gt_u32 s20, 0x37f
	s_cbranch_scc0 .LBB0_744
	s_add_i32 s11, s20, 0xfc80
	s_and_b32 s12, s11, 0xffff
	s_mul_i32 s12, s12, 0xaaab
	s_lshr_b32 s12, s12, 26
	s_mul_i32 s13, s12, 0x600
	s_sub_i32 s11, s11, s13
	s_and_b32 s23, s11, 0xffff
	s_lshl_b32 s11, s10, 4
	s_add_i32 s16, s11, s12
	s_ashr_i32 s17, s16, 31
	s_cmpk_gt_u32 s23, 0x1ff
	s_mov_b64 s[18:19], -1
	s_cbranch_scc0 .LBB0_741
	s_lshl_b64 s[18:19], s[16:17], 23
	s_cmpk_gt_u32 s23, 0x3ff
	s_mov_b64 s[14:15], -1
	s_cbranch_scc0 .LBB0_738
	v_readlane_b32 s24, v238, 25
	s_add_i32 s11, s23, 0xfffffc00
	v_readlane_b32 s30, v238, 31
	v_readlane_b32 s31, v238, 32
	s_add_u32 s12, s30, s18
	v_readlane_b32 s25, v238, 26
	v_readlane_b32 s26, v238, 27
	v_readlane_b32 s27, v238, 28
	v_readlane_b32 s28, v238, 29
	v_readlane_b32 s29, v238, 30
	s_addc_u32 s13, s31, s19
	s_lshr_b32 s21, s11, 4
	s_and_b32 s11, s23, 15
	s_mov_b64 s[14:15], 0
